# A-B of the static priority raise for waves 4-7 in the (now symmetric) attention loop: raise removed
# baseline (speedup 1.0000x reference)
; __global__ void __launch_bounds__(512, 2) trunk_fwd(Args args) {
;     ...
;             if (wave >= 4) __builtin_amdgcn_s_setprio(1);
;             if (G == 256) {
.LBB0_810:
	s_setprio 0
	s_cmpk_eq_i32 s51, 0x100
	s_mov_b64 s[0:1], -1
	s_cbranch_scc1 .LBB0_809
